# row-sum chain starts with x1+x0 instead of 0+x0 (one VALU less per KV tile, bit-identical)
# baseline (speedup 1.0000x reference)
; #define SBAR() __builtin_amdgcn_sched_barrier(0)
; #define KWRITE(b, src0, src1) do { if constexpr (ND0 == 4) { *(bf16x8*)(K_lds + (b) * SHM_K + KSWZ(kr, kcb)) = src0; } \
;     else { int kc = sc * 2; *(bf16x8*)(K_lds + (b) * SHM_K + KSWZ(sr, kc)) = src0; *(bf16x8*)(K_lds + (b) * SHM_K + KSWZ(32 + sr, kc)) = src1; } } while (0)
; #define SLOAD_B(k0) do { vs0b = *reinterpret_cast<const bf16x8*>(&Vh[(long)((k0) + sr) * LDK + sc]); vs1b = *reinterpret_cast<const bf16x8*>(&Vh[(long)((k0) + 32 + sr) * LDK + sc]); KLOAD(ks0b, ks1b, k0); } while (0)
; #define PSM(P0, P1, MN, AL) do { if constexpr (PRE) partialSM_pre(P0, P1, m_reg, AL, 11.541560327111707f); else partialSM(P0, P1, m_reg, MN, AL, C, thr_raw); } while (0)
; __device__ __forceinline__ void finishSM(f32x16& p0, f32x16& p1, float alpha, float& l_reg, bf16x8& pa0, bf16x8& pa1, bf16x8& pa2, bf16x8& pa3) {
; #pragma unroll
;   for (int r = 0; r < 16; ++r) p1[r] = __builtin_amdgcn_exp2f(p1[r]);
;   float ps = 0;
; #pragma unroll
;   for (int r = 0; r < 16; ++r) ps += p0[r];
; #pragma unroll
;   for (int r = 0; r < 16; ++r) ps += p1[r];
;   { auto rr = __builtin_amdgcn_permlane32_swap(__float_as_uint(ps), __float_as_uint(ps), false, false);
;     ps = __uint_as_float(rr[0]) + __uint_as_float(rr[1]); }
;   l_reg = l_reg * alpha + ps;
;     ...
;   PK4(p0, 0, pa0); PK4(p0, 8, pa1); PK4(p1, 0, pa2); PK4(p1, 8, pa3);
;     ...
; }
; template <int ND0>
; __device__ __forceinline__ void qkt(f32x16& p0, f32x16& p1, const char* Ks, const bf16x8* qr, int r32, int hi) {
;   p0 = f32x16{}; p1 = f32x16{};
; #pragma unroll
;   for (int d0 = 0; d0 < ND0; ++d0) { int cb = (d0 * 16 + hi * 8) * 2;
;     bf16x8 b0 = *reinterpret_cast<const bf16x8*>(Ks + KSWZ(r32, cb));
;     bf16x8 b1 = *reinterpret_cast<const bf16x8*>(Ks + KSWZ(32 + r32, cb));
;     p0 = __builtin_amdgcn_mfma_f32_32x32x16_bf16(b0, qr[d0], p0, 0, 0, 0);
;     p1 = __builtin_amdgcn_mfma_f32_32x32x16_bf16(b1, qr[d0], p1, 0, 0, 0); }
; }
; template <int ND0, int LDQ, int LDK, int LDO> ...
;     ...
;     SBAR(); qkt<ND0>(pB0, pB1, Kq1, qr, r32, hi);
;     finishSM(pA0, pA1, alA, l_reg, pa0, pa1, pa2, pa3); SBAR();
;     SLOAD_B((j + 2) * KVBLK); SBAR();
;     pv_d0(o, vb0, pa0, pa1, pa2, pa3); KWRITE(0, ks0a, ks1a); PSM(pB0, pB1, mnB, alB);
.LBB0_146:
	ds_read_b128 v[208:211], v200 offset:49152
	ds_read_b128 v[214:217], v200 offset:57344
	v_exp_f32_e32 v170, v64
	s_waitcnt lgkmcnt(2)
	v_mfma_f32_32x32x16_bf16 v[96:111], v[80:83], v[114:117], 0
	v_add_f32_e32 v64, v213, v176
	v_add_f32_e32 v64, v174, v64
	v_add_f32_e32 v64, v177, v64
	v_add_f32_e32 v64, v173, v64
	v_add_f32_e32 v64, v175, v64
	v_add_f32_e32 v64, v171, v64
	v_add_f32_e32 v64, v172, v64
	v_mfma_f32_32x32x16_bf16 v[80:95], v[84:87], v[114:117], 0
	v_add_f32_e32 v64, v167, v64
	v_add_f32_e32 v64, v169, v64
	v_add_f32_e32 v64, v166, v64
	v_add_f32_e32 v64, v168, v64
	v_add_f32_e32 v64, v163, v64
	v_add_f32_e32 v64, v165, v64
	v_add_f32_e32 v64, v162, v64
	s_waitcnt lgkmcnt(0)
	v_mfma_f32_32x32x16_bf16 v[96:111], v[208:211], v[122:125], v[96:111]
	v_exp_f32_e32 v212, v67
	v_add_f32_e32 v64, v164, v64
	v_add_f32_e32 v64, v170, v64
	v_exp_f32_e32 v218, v72
	v_exp_f32_e32 v219, v73
	v_exp_f32_e32 v220, v74
	v_exp_f32_e32 v221, v75
	v_mfma_f32_32x32x16_bf16 v[80:95], v[214:217], v[122:125], v[80:95]
	ds_read_b128 v[208:211], v202 offset:49152
	ds_read_b128 v[214:217], v202 offset:57344
	v_exp_f32_e32 v222, v76
	v_exp_f32_e32 v223, v77
	v_exp_f32_e32 v224, v78
	v_exp_f32_e32 v79, v79
	s_waitcnt lgkmcnt(0)
	v_mfma_f32_32x32x16_bf16 v[96:111], v[208:211], v[142:145], v[96:111]
	v_mfma_f32_32x32x16_bf16 v[80:95], v[214:217], v[142:145], v[80:95]
	ds_read_b128 v[208:211], v201 offset:49152
	ds_read_b128 v[214:217], v201 offset:57344
	s_waitcnt lgkmcnt(0)
	v_mfma_f32_32x32x16_bf16 v[96:111], v[208:211], v[138:141], v[96:111]
	v_mfma_f32_32x32x16_bf16 v[80:95], v[214:217], v[138:141], v[80:95]
	ds_read_b128 v[208:211], v203 offset:49152
	ds_read_b128 v[214:217], v203 offset:57344
	s_waitcnt lgkmcnt(0)
	v_mfma_f32_32x32x16_bf16 v[96:111], v[208:211], v[134:137], v[96:111]
	v_mfma_f32_32x32x16_bf16 v[80:95], v[214:217], v[134:137], v[80:95]
	ds_read_b128 v[208:211], v204 offset:49152
	ds_read_b128 v[214:217], v204 offset:57344
	s_waitcnt lgkmcnt(0)
	v_mfma_f32_32x32x16_bf16 v[96:111], v[208:211], v[130:133], v[96:111]
	v_mfma_f32_32x32x16_bf16 v[80:95], v[214:217], v[130:133], v[80:95]
	ds_read_b128 v[208:211], v206 offset:49152
	ds_read_b128 v[214:217], v206 offset:57344
	s_waitcnt lgkmcnt(0)
	v_mfma_f32_32x32x16_bf16 v[96:111], v[208:211], v[126:129], v[96:111]
	v_mfma_f32_32x32x16_bf16 v[80:95], v[214:217], v[126:129], v[80:95]
	ds_read_b128 v[208:211], v205 offset:49152
	ds_read_b128 v[214:217], v205 offset:57344
	s_waitcnt lgkmcnt(0)
	v_mfma_f32_32x32x16_bf16 v[96:111], v[208:211], v[118:121], v[96:111]
	v_exp_f32_e32 v210, v65
	v_exp_f32_e32 v211, v66
	v_add_f32_e32 v64, v210, v64
	v_add_f32_e32 v64, v211, v64
	v_add_f32_e32 v64, v212, v64
	v_mfma_f32_32x32x16_bf16 v[80:95], v[214:217], v[118:121], v[80:95]
	v_exp_f32_e32 v214, v68
	v_exp_f32_e32 v215, v69
	v_exp_f32_e32 v216, v70
	v_exp_f32_e32 v217, v71
	v_add_f32_e32 v64, v214, v64
	v_add_f32_e32 v64, v215, v64
	v_add_f32_e32 v64, v216, v64
	v_add_f32_e32 v64, v217, v64
	v_add_f32_e32 v64, v218, v64
	v_add_f32_e32 v64, v219, v64
	v_add_f32_e32 v64, v220, v64
	v_add_f32_e32 v64, v221, v64
	v_add_f32_e32 v64, v222, v64
	v_add_f32_e32 v64, v223, v64
	v_add_f32_e32 v64, v224, v64
	v_add_f32_e32 v208, v79, v64
	v_mov_b32_e32 v209, v208
	v_cvt_pk_bf16_f32 v64, v176, v213
	v_cvt_pk_bf16_f32 v65, v174, v177
	v_cvt_pk_bf16_f32 v66, v173, v175
	v_cvt_pk_bf16_f32 v67, v171, v172
	v_cvt_pk_bf16_f32 v68, v167, v169
	v_cvt_pk_bf16_f32 v69, v166, v168
	v_cvt_pk_bf16_f32 v70, v163, v165
	v_cvt_pk_bf16_f32 v71, v162, v164
	v_cvt_pk_bf16_f32 v72, v170, v210
	v_cvt_pk_bf16_f32 v73, v211, v212
	v_cvt_pk_bf16_f32 v74, v214, v215
	v_cvt_pk_bf16_f32 v75, v216, v217
	v_cvt_pk_bf16_f32 v76, v218, v219
	v_cvt_pk_bf16_f32 v77, v220, v221
	v_cvt_pk_bf16_f32 v78, v222, v223
	v_cvt_pk_bf16_f32 v79, v224, v79
	v_permlane32_swap_b32_e32 v208, v209
	v_permlane32_swap_b32_e32 v64, v66
	v_permlane32_swap_b32_e32 v65, v67
	v_permlane32_swap_b32_e32 v68, v70
	v_permlane32_swap_b32_e32 v69, v71
	v_permlane32_swap_b32_e32 v72, v74
	v_permlane32_swap_b32_e32 v73, v75
	v_permlane32_swap_b32_e32 v76, v78
	v_permlane32_swap_b32_e32 v77, v79
	s_mov_b32 s4, 0xfffb8000
	v_add_co_u32_e32 v166, vcc, s4, v188
	s_mov_b32 s4, 0xfffd0000
	s_nop 0
	v_addc_co_u32_e32 v167, vcc, -1, v189, vcc
	v_add_co_u32_e32 v174, vcc, s4, v188
	s_nop 1
	v_addc_co_u32_e32 v175, vcc, -1, v189, vcc
	global_load_dwordx4 v[162:165], v[166:167], off
	global_load_dwordx4 v[170:173], v[166:167], off offset:-512
	global_load_dwordx4 v[166:169], v[174:175], off
	global_load_dwordx4 v[174:177], v[174:175], off offset:-512
	v_cmp_neq_f32_e32 vcc, 0, v193
	ds_read_b64_tr_b16 v[210:211], v194 offset:0
	ds_read_b64_tr_b16 v[212:213], v194 offset:0x800
	ds_read_b64_tr_b16 v[214:215], v194 offset:0x1000
	ds_read_b64_tr_b16 v[216:217], v194 offset:0x1800
	ds_read_b64_tr_b16 v[218:219], v194 offset:0x2000
	ds_read_b64_tr_b16 v[220:221], v194 offset:0x2800
	ds_read_b64_tr_b16 v[222:223], v194 offset:0x3000
	ds_read_b64_tr_b16 v[224:225], v194 offset:0x3800
	s_cbranch_vccnz .LBB0_163

; #define SBAR() __builtin_amdgcn_sched_barrier(0)
; #define SLOAD_A(k0) do { vs0a = *reinterpret_cast<const bf16x8*>(&Vh[(long)((k0) + sr) * LDK + sc]); vs1a = *reinterpret_cast<const bf16x8*>(&Vh[(long)((k0) + 32 + sr) * LDK + sc]); KLOAD(ks0a, ks1a, k0); } while (0)
; __device__ __forceinline__ void finishSM(f32x16& p0, f32x16& p1, float alpha, float& l_reg, bf16x8& pa0, bf16x8& pa1, bf16x8& pa2, bf16x8& pa3) {
; #pragma unroll
;   for (int r = 0; r < 16; ++r) p1[r] = __builtin_amdgcn_exp2f(p1[r]);
;   float ps = 0;
; #pragma unroll
;   for (int r = 0; r < 16; ++r) ps += p0[r];
; #pragma unroll
;   for (int r = 0; r < 16; ++r) ps += p1[r];
;   { auto rr = __builtin_amdgcn_permlane32_swap(__float_as_uint(ps), __float_as_uint(ps), false, false);
;     ps = __uint_as_float(rr[0]) + __uint_as_float(rr[1]); }
;   l_reg = l_reg * alpha + ps;
;     ...
;   PK4(p0, 0, pa0); PK4(p0, 8, pa1); PK4(p1, 0, pa2); PK4(p1, 8, pa3);
;     ...
; }
; template <int ND0>
; __device__ __forceinline__ void qkt(f32x16& p0, f32x16& p1, const char* Ks, const bf16x8* qr, int r32, int hi) {
;   p0 = f32x16{}; p1 = f32x16{};
; #pragma unroll
;   for (int d0 = 0; d0 < ND0; ++d0) { int cb = (d0 * 16 + hi * 8) * 2;
;     bf16x8 b0 = *reinterpret_cast<const bf16x8*>(Ks + KSWZ(r32, cb));
;     bf16x8 b1 = *reinterpret_cast<const bf16x8*>(Ks + KSWZ(32 + r32, cb));
;     p0 = __builtin_amdgcn_mfma_f32_32x32x16_bf16(b0, qr[d0], p0, 0, 0, 0);
;     p1 = __builtin_amdgcn_mfma_f32_32x32x16_bf16(b1, qr[d0], p1, 0, 0, 0); }
; }
; template <int ND0, int LDQ, int LDK, int LDO> ...
;     ...
;     SBAR(); qkt<ND0>(pA0, pA1, Kq0, qr, r32, hi);
;     finishSM(pB0, pB1, alB, l_reg, pa0, pa1, pa2, pa3); SBAR();
;     if (j + 3 < NT) SLOAD_A((j + 3) * KVBLK); SBAR();
.LBB0_153:
	v_mov_b32_e32 v242, 0x800
	ds_read_b128 v[238:241], v200 offset:32768
	ds_read_b128 v[234:237], v200 offset:40960
	v_exp_f32_e32 v245, v88
	v_exp_f32_e32 v246, v89
	s_waitcnt lgkmcnt(2)
	v_mfma_f32_32x32x16_bf16 v[96:111], v[64:67], v[114:117], 0
	v_exp_f32_e32 v247, v90
	v_exp_f32_e32 v231, v91
	v_exp_f32_e32 v243, v92
	v_exp_f32_e32 v252, v93
	v_exp_f32_e32 v253, v94
	v_exp_f32_e32 v95, v95
	v_mfma_f32_32x32x16_bf16 v[64:79], v[68:71], v[114:117], 0
	s_waitcnt lgkmcnt(0)
	v_mfma_f32_32x32x16_bf16 v[96:111], v[238:241], v[122:125], v[96:111]
	v_mfma_f32_32x32x16_bf16 v[64:79], v[234:237], v[122:125], v[64:79]
	ds_read_b128 v[234:237], v202 offset:32768
	ds_read_b128 v[238:241], v202 offset:40960
	s_waitcnt lgkmcnt(0)
	v_mfma_f32_32x32x16_bf16 v[96:111], v[234:237], v[142:145], v[96:111]
	v_mfma_f32_32x32x16_bf16 v[64:79], v[238:241], v[142:145], v[64:79]
	ds_read_b128 v[234:237], v201 offset:32768
	ds_read_b128 v[238:241], v201 offset:40960
	s_waitcnt lgkmcnt(0)
	v_mfma_f32_32x32x16_bf16 v[96:111], v[234:237], v[138:141], v[96:111]
	v_mfma_f32_32x32x16_bf16 v[64:79], v[238:241], v[138:141], v[64:79]
	ds_read_b128 v[234:237], v203 offset:32768
	ds_read_b128 v[238:241], v203 offset:40960
	s_waitcnt lgkmcnt(0)
	v_mfma_f32_32x32x16_bf16 v[96:111], v[234:237], v[134:137], v[96:111]
	v_mfma_f32_32x32x16_bf16 v[64:79], v[238:241], v[134:137], v[64:79]
	ds_read_b128 v[234:237], v204 offset:32768
	ds_read_b128 v[238:241], v204 offset:40960
	s_waitcnt lgkmcnt(0)
	v_mfma_f32_32x32x16_bf16 v[96:111], v[234:237], v[130:133], v[96:111]
	v_mfma_f32_32x32x16_bf16 v[64:79], v[238:241], v[130:133], v[64:79]
	ds_read_b128 v[234:237], v206 offset:32768
	ds_read_b128 v[238:241], v206 offset:40960
	s_waitcnt lgkmcnt(0)
	v_mfma_f32_32x32x16_bf16 v[96:111], v[234:237], v[126:129], v[96:111]
	v_mfma_f32_32x32x16_bf16 v[64:79], v[238:241], v[126:129], v[64:79]
	ds_read_b128 v[234:237], v205 offset:32768
	ds_read_b128 v[238:241], v205 offset:40960
	s_waitcnt lgkmcnt(0)
	v_mfma_f32_32x32x16_bf16 v[96:111], v[234:237], v[118:121], v[96:111]
	v_exp_f32_e32 v234, v80
	v_add_f32_e32 v80, v244, v226
	v_add_f32_e32 v80, v224, v80
	v_add_f32_e32 v80, v227, v80
	v_add_f32_e32 v80, v223, v80
	v_add_f32_e32 v80, v225, v80
	v_add_f32_e32 v80, v221, v80
	v_add_f32_e32 v80, v222, v80
	v_add_f32_e32 v80, v218, v80
	v_add_f32_e32 v80, v220, v80
	v_add_f32_e32 v80, v217, v80
	v_add_f32_e32 v80, v219, v80
	v_add_f32_e32 v80, v214, v80
	v_exp_f32_e32 v235, v81
	v_add_f32_e32 v80, v216, v80
	v_exp_f32_e32 v236, v82
	v_add_f32_e32 v80, v213, v80
	v_exp_f32_e32 v237, v83
	v_add_f32_e32 v80, v215, v80
	v_mfma_f32_32x32x16_bf16 v[64:79], v[238:241], v[118:121], v[64:79]
	v_exp_f32_e32 v238, v84
	v_add_f32_e32 v80, v234, v80
	v_exp_f32_e32 v239, v85
	v_add_f32_e32 v80, v235, v80
	v_exp_f32_e32 v240, v86
	v_add_f32_e32 v80, v236, v80
	v_exp_f32_e32 v241, v87
	v_add_f32_e32 v80, v237, v80
	v_add_f32_e32 v80, v238, v80
	v_add_f32_e32 v80, v239, v80
	v_add_f32_e32 v80, v240, v80
	v_add_f32_e32 v80, v241, v80
	v_add_f32_e32 v80, v245, v80
	v_add_f32_e32 v80, v246, v80
	v_add_f32_e32 v80, v247, v80
	v_add_f32_e32 v80, v231, v80
	v_add_f32_e32 v80, v243, v80
	v_add_f32_e32 v80, v252, v80
	v_add_f32_e32 v80, v253, v80
	v_add_f32_e32 v211, v95, v80
	v_mov_b32_e32 v212, v211
	v_cvt_pk_bf16_f32 v80, v226, v244
	v_cvt_pk_bf16_f32 v81, v224, v227
	v_cvt_pk_bf16_f32 v82, v223, v225
	v_cvt_pk_bf16_f32 v83, v221, v222
	v_cvt_pk_bf16_f32 v84, v218, v220
	v_cvt_pk_bf16_f32 v85, v217, v219
	v_cvt_pk_bf16_f32 v86, v214, v216
	v_cvt_pk_bf16_f32 v87, v213, v215
	v_cvt_pk_bf16_f32 v88, v234, v235
	v_cvt_pk_bf16_f32 v89, v236, v237
	v_cvt_pk_bf16_f32 v90, v238, v239
	v_cvt_pk_bf16_f32 v91, v240, v241
	v_cvt_pk_bf16_f32 v92, v245, v246
	v_cvt_pk_bf16_f32 v93, v247, v231
	v_cvt_pk_bf16_f32 v94, v243, v252
	v_cvt_pk_bf16_f32 v95, v253, v95
	v_permlane32_swap_b32_e32 v211, v212
	v_permlane32_swap_b32_e32 v80, v82
	v_permlane32_swap_b32_e32 v81, v83
	v_permlane32_swap_b32_e32 v84, v86
	v_permlane32_swap_b32_e32 v85, v87
	v_permlane32_swap_b32_e32 v88, v90
	v_permlane32_swap_b32_e32 v89, v91
	v_permlane32_swap_b32_e32 v92, v94
	v_permlane32_swap_b32_e32 v93, v95
	s_add_i32 s39, s39, 2
	s_cmp_ge_u32 s39, s38
	s_cselect_b64 s[4:5], -1, 0
	s_and_b64 vcc, exec, s[4:5]
	s_cbranch_vccnz .Lgqa_pf_skip
	v_add_co_u32_e32 v146, vcc, 0xfffe8000, v188
	s_nop 1
	v_addc_co_u32_e32 v147, vcc, -1, v189, vcc
	global_load_dwordx4 v[158:161], v[146:147], off
	global_load_dwordx4 v[150:153], v[146:147], off offset:-512
	global_load_dwordx4 v[154:157], v[188:189], off
	global_load_dwordx4 v[146:149], v[188:189], off offset:-512

; #define SBAR() __builtin_amdgcn_sched_barrier(0)
; #define KWRITE(b, src0, src1) do { if constexpr (ND0 == 4) { *(bf16x8*)(K_lds + (b) * SHM_K + KSWZ(kr, kcb)) = src0; } \
;     else { int kc = sc * 2; *(bf16x8*)(K_lds + (b) * SHM_K + KSWZ(sr, kc)) = src0; *(bf16x8*)(K_lds + (b) * SHM_K + KSWZ(32 + sr, kc)) = src1; } } while (0)
; #define SLOAD_B(k0) do { vs0b = *reinterpret_cast<const bf16x8*>(&Vh[(long)((k0) + sr) * LDK + sc]); vs1b = *reinterpret_cast<const bf16x8*>(&Vh[(long)((k0) + 32 + sr) * LDK + sc]); KLOAD(ks0b, ks1b, k0); } while (0)
; #define PSM(P0, P1, MN, AL) do { if constexpr (PRE) partialSM_pre(P0, P1, m_reg, AL, 11.541560327111707f); else partialSM(P0, P1, m_reg, MN, AL, C, thr_raw); } while (0)
; __device__ __forceinline__ void finishSM(f32x16& p0, f32x16& p1, float alpha, float& l_reg, bf16x8& pa0, bf16x8& pa1, bf16x8& pa2, bf16x8& pa3) {
; #pragma unroll
;   for (int r = 0; r < 16; ++r) p1[r] = __builtin_amdgcn_exp2f(p1[r]);
;   float ps = 0;
; #pragma unroll
;   for (int r = 0; r < 16; ++r) ps += p0[r];
; #pragma unroll
;   for (int r = 0; r < 16; ++r) ps += p1[r];
;   { auto rr = __builtin_amdgcn_permlane32_swap(__float_as_uint(ps), __float_as_uint(ps), false, false);
;     ps = __uint_as_float(rr[0]) + __uint_as_float(rr[1]); }
;   l_reg = l_reg * alpha + ps;
;     ...
;   PK4(p0, 0, pa0); PK4(p0, 8, pa1); PK4(p1, 0, pa2); PK4(p1, 8, pa3);
;     ...
; }
; template <int ND0>
; __device__ __forceinline__ void qkt(f32x16& p0, f32x16& p1, const char* Ks, const bf16x8* qr, int r32, int hi) {
;   p0 = f32x16{}; p1 = f32x16{};
; #pragma unroll
;   for (int d0 = 0; d0 < ND0; ++d0) { int cb = (d0 * 16 + hi * 8) * 2;
;     bf16x8 b0 = *reinterpret_cast<const bf16x8*>(Ks + KSWZ(r32, cb));
;     bf16x8 b1 = *reinterpret_cast<const bf16x8*>(Ks + KSWZ(32 + r32, cb));
;     p0 = __builtin_amdgcn_mfma_f32_32x32x16_bf16(b0, qr[d0], p0, 0, 0, 0);
;     p1 = __builtin_amdgcn_mfma_f32_32x32x16_bf16(b1, qr[d0], p1, 0, 0, 0); }
; }
; template <int ND0, int LDQ, int LDK, int LDO> ...
;     ...
;     SBAR(); qkt<ND0>(pB0, pB1, Kq1, qr, r32, hi);
;     finishSM(pA0, pA1, alA, l_reg, pa0, pa1, pa2, pa3); SBAR();
;     SLOAD_B((j + 2) * KVBLK); SBAR();
;     pv_d0(o, vb0, pa0, pa1, pa2, pa3); KWRITE(0, ks0a, ks1a); PSM(pB0, pB1, mnB, alB);
.LBB0_214:
	ds_read_b128 v[202:205], v198 offset:49152
	ds_read_b128 v[208:211], v198 offset:57344
	ds_read_b128 v[222:225], v199 offset:49152
	ds_read_b128 v[234:237], v199 offset:57344
	ds_read_b128 v[238:241], v196 offset:49152
	ds_read_b128 v[244:247], v196 offset:57344
	v_exp_f32_e32 v150, v64
	s_waitcnt lgkmcnt(6)
	v_mfma_f32_32x32x16_bf16 v[96:111], v[80:83], v[126:129], 0
	v_add_f32_e32 v64, v206, v176
	v_add_f32_e32 v64, v174, v64
	v_add_f32_e32 v64, v177, v64
	v_add_f32_e32 v64, v152, v64
	v_add_f32_e32 v64, v175, v64
	v_add_f32_e32 v64, v151, v64
	v_add_f32_e32 v64, v153, v64
	v_mfma_f32_32x32x16_bf16 v[80:95], v[84:87], v[126:129], 0
	v_add_f32_e32 v64, v147, v64
	v_add_f32_e32 v64, v149, v64
	v_add_f32_e32 v64, v145, v64
	v_add_f32_e32 v64, v148, v64
	v_add_f32_e32 v64, v143, v64
	v_add_f32_e32 v64, v146, v64
	v_add_f32_e32 v64, v142, v64
	s_waitcnt lgkmcnt(4)
	v_mfma_f32_32x32x16_bf16 v[96:111], v[202:205], v[122:125], v[96:111]
	v_add_f32_e32 v64, v144, v64
	v_exp_f32_e32 v207, v68
	v_add_f32_e32 v64, v150, v64
	v_exp_f32_e32 v212, v73
	v_exp_f32_e32 v213, v74
	v_exp_f32_e32 v214, v75
	v_exp_f32_e32 v215, v76
	v_mfma_f32_32x32x16_bf16 v[80:95], v[208:211], v[122:125], v[80:95]
	v_exp_f32_e32 v216, v77
	v_exp_f32_e32 v217, v78
	v_exp_f32_e32 v79, v79
	s_waitcnt lgkmcnt(2)
	v_mfma_f32_32x32x16_bf16 v[96:111], v[222:225], v[118:121], v[96:111]
	v_mfma_f32_32x32x16_bf16 v[80:95], v[234:237], v[118:121], v[80:95]
	s_waitcnt lgkmcnt(0)
	v_mfma_f32_32x32x16_bf16 v[96:111], v[238:241], v[114:117], v[96:111]
	v_exp_f32_e32 v203, v65
	v_exp_f32_e32 v204, v66
	v_exp_f32_e32 v205, v67
	v_add_f32_e32 v64, v203, v64
	v_add_f32_e32 v64, v204, v64
	v_add_f32_e32 v64, v205, v64
	v_mfma_f32_32x32x16_bf16 v[80:95], v[244:247], v[114:117], v[80:95]
	v_exp_f32_e32 v208, v69
	v_exp_f32_e32 v209, v70
	v_exp_f32_e32 v210, v71
	v_exp_f32_e32 v211, v72
	v_add_f32_e32 v64, v207, v64
	v_add_f32_e32 v64, v208, v64
	v_add_f32_e32 v64, v209, v64
	v_add_f32_e32 v64, v210, v64
	v_add_f32_e32 v64, v211, v64
	v_add_f32_e32 v64, v212, v64
	v_add_f32_e32 v64, v213, v64
	v_add_f32_e32 v64, v214, v64
	v_add_f32_e32 v64, v215, v64
	v_add_f32_e32 v64, v216, v64
	v_add_f32_e32 v64, v217, v64
	v_add_f32_e32 v201, v79, v64
	v_mov_b32_e32 v202, v201
	v_cvt_pk_bf16_f32 v64, v176, v206
	v_cvt_pk_bf16_f32 v65, v174, v177
	v_cvt_pk_bf16_f32 v66, v152, v175
	v_cvt_pk_bf16_f32 v67, v151, v153
	v_cvt_pk_bf16_f32 v68, v147, v149
	v_cvt_pk_bf16_f32 v69, v145, v148
	v_cvt_pk_bf16_f32 v70, v143, v146
	v_cvt_pk_bf16_f32 v71, v142, v144
	v_cvt_pk_bf16_f32 v72, v150, v203
	v_cvt_pk_bf16_f32 v73, v204, v205
	v_cvt_pk_bf16_f32 v74, v207, v208
	v_cvt_pk_bf16_f32 v75, v209, v210
	v_cvt_pk_bf16_f32 v76, v211, v212
	v_cvt_pk_bf16_f32 v77, v213, v214
	v_cvt_pk_bf16_f32 v78, v215, v216
	v_cvt_pk_bf16_f32 v79, v217, v79
	v_permlane32_swap_b32_e32 v201, v202
	v_permlane32_swap_b32_e32 v64, v66
	v_permlane32_swap_b32_e32 v65, v67
	v_permlane32_swap_b32_e32 v68, v70
	v_permlane32_swap_b32_e32 v69, v71
	v_permlane32_swap_b32_e32 v72, v74
	v_permlane32_swap_b32_e32 v73, v75
	v_permlane32_swap_b32_e32 v76, v78
	v_permlane32_swap_b32_e32 v77, v79
	global_load_dwordx4 v[142:145], v[172:173], off
	v_lshl_add_u64 v[174:175], v[172:173], 0, s[34:35]
	global_load_dwordx4 v[146:149], v[174:175], off
	global_load_dwordx4 v[150:153], v[170:171], off offset:2048
	v_lshl_add_u64 v[172:173], v[172:173], 0, s[46:47]
	v_lshl_add_u64 v[170:171], v[170:171], 0, s[46:47]
	v_cmp_neq_f32_e32 vcc, 0, v191
	ds_read_b64_tr_b16 v[204:205], v192 offset:0
	ds_read_b64_tr_b16 v[206:207], v192 offset:0x800
	ds_read_b64_tr_b16 v[208:209], v192 offset:0x1000
	ds_read_b64_tr_b16 v[210:211], v192 offset:0x1800
	ds_read_b64_tr_b16 v[212:213], v192 offset:0x2000
	ds_read_b64_tr_b16 v[214:215], v192 offset:0x2800
	ds_read_b64_tr_b16 v[216:217], v192 offset:0x3000
	ds_read_b64_tr_b16 v[218:219], v192 offset:0x3800
	s_cbranch_vccnz .LBB0_230

; #define SBAR() __builtin_amdgcn_sched_barrier(0)
; #define SLOAD_A(k0) do { vs0a = *reinterpret_cast<const bf16x8*>(&Vh[(long)((k0) + sr) * LDK + sc]); vs1a = *reinterpret_cast<const bf16x8*>(&Vh[(long)((k0) + 32 + sr) * LDK + sc]); KLOAD(ks0a, ks1a, k0); } while (0)
; __device__ __forceinline__ void finishSM(f32x16& p0, f32x16& p1, float alpha, float& l_reg, bf16x8& pa0, bf16x8& pa1, bf16x8& pa2, bf16x8& pa3) {
; #pragma unroll
;   for (int r = 0; r < 16; ++r) p1[r] = __builtin_amdgcn_exp2f(p1[r]);
;   float ps = 0;
; #pragma unroll
;   for (int r = 0; r < 16; ++r) ps += p0[r];
; #pragma unroll
;   for (int r = 0; r < 16; ++r) ps += p1[r];
;   { auto rr = __builtin_amdgcn_permlane32_swap(__float_as_uint(ps), __float_as_uint(ps), false, false);
;     ps = __uint_as_float(rr[0]) + __uint_as_float(rr[1]); }
;   l_reg = l_reg * alpha + ps;
;     ...
;   PK4(p0, 0, pa0); PK4(p0, 8, pa1); PK4(p1, 0, pa2); PK4(p1, 8, pa3);
;     ...
; }
; template <int ND0>
; __device__ __forceinline__ void qkt(f32x16& p0, f32x16& p1, const char* Ks, const bf16x8* qr, int r32, int hi) {
;   p0 = f32x16{}; p1 = f32x16{};
; #pragma unroll
;   for (int d0 = 0; d0 < ND0; ++d0) { int cb = (d0 * 16 + hi * 8) * 2;
;     bf16x8 b0 = *reinterpret_cast<const bf16x8*>(Ks + KSWZ(r32, cb));
;     bf16x8 b1 = *reinterpret_cast<const bf16x8*>(Ks + KSWZ(32 + r32, cb));
;     p0 = __builtin_amdgcn_mfma_f32_32x32x16_bf16(b0, qr[d0], p0, 0, 0, 0);
;     p1 = __builtin_amdgcn_mfma_f32_32x32x16_bf16(b1, qr[d0], p1, 0, 0, 0); }
; }
; template <int ND0, int LDQ, int LDK, int LDO> ...
;     ...
;     SBAR(); qkt<ND0>(pA0, pA1, Kq0, qr, r32, hi);
;     finishSM(pB0, pB1, alB, l_reg, pa0, pa1, pa2, pa3); SBAR();
;     if (j + 3 < NT) SLOAD_A((j + 3) * KVBLK); SBAR();
.LBB0_220:
	ds_read_b128 v[222:225], v198 offset:32768
	ds_read_b128 v[244:247], v198 offset:40960
	ds_read_b128 v[130:133], v199 offset:32768
	ds_read_b128 v[134:137], v199 offset:40960
	ds_read_b128 v[138:141], v196 offset:32768
	v_exp_f32_e32 v226, v84
	v_exp_f32_e32 v227, v85
	s_waitcnt lgkmcnt(5)
	v_mfma_f32_32x32x16_bf16 v[96:111], v[64:67], v[126:129], 0
	v_exp_f32_e32 v234, v86
	v_exp_f32_e32 v235, v87
	v_exp_f32_e32 v236, v88
	v_exp_f32_e32 v237, v89
	v_exp_f32_e32 v238, v90
	v_exp_f32_e32 v239, v91
	v_exp_f32_e32 v240, v92
	v_mfma_f32_32x32x16_bf16 v[64:79], v[68:71], v[126:129], 0
	v_exp_f32_e32 v241, v93
	v_exp_f32_e32 v95, v95
	s_waitcnt lgkmcnt(3)
	v_mfma_f32_32x32x16_bf16 v[96:111], v[222:225], v[122:125], v[96:111]
	v_mfma_f32_32x32x16_bf16 v[64:79], v[244:247], v[122:125], v[64:79]
	ds_read_b128 v[244:247], v196 offset:40960
	s_waitcnt lgkmcnt(2)
	v_mfma_f32_32x32x16_bf16 v[96:111], v[130:133], v[118:121], v[96:111]
	v_mfma_f32_32x32x16_bf16 v[64:79], v[134:137], v[118:121], v[64:79]
	s_waitcnt lgkmcnt(0)
	v_mfma_f32_32x32x16_bf16 v[96:111], v[138:141], v[114:117], v[96:111]
	v_exp_f32_e32 v222, v80
	v_add_f32_e32 v80, v221, v219
	v_add_f32_e32 v80, v217, v80
	v_add_f32_e32 v80, v220, v80
	v_add_f32_e32 v80, v215, v80
	v_add_f32_e32 v80, v218, v80
	v_add_f32_e32 v80, v214, v80
	v_add_f32_e32 v80, v216, v80
	v_add_f32_e32 v80, v211, v80
	v_add_f32_e32 v80, v213, v80
	v_add_f32_e32 v80, v209, v80
	v_add_f32_e32 v80, v212, v80
	v_add_f32_e32 v80, v207, v80
	v_exp_f32_e32 v223, v81
	v_add_f32_e32 v80, v210, v80
	v_exp_f32_e32 v224, v82
	v_add_f32_e32 v80, v206, v80
	v_exp_f32_e32 v225, v83
	v_add_f32_e32 v80, v208, v80
	v_add_f32_e32 v80, v222, v80
	v_add_f32_e32 v80, v223, v80
	v_add_f32_e32 v80, v224, v80
	v_add_f32_e32 v80, v225, v80
	v_add_f32_e32 v80, v226, v80
	v_add_f32_e32 v80, v227, v80
	v_add_f32_e32 v80, v234, v80
	v_add_f32_e32 v80, v235, v80
	v_add_f32_e32 v80, v236, v80
	v_add_f32_e32 v80, v237, v80
	v_mfma_f32_32x32x16_bf16 v[64:79], v[244:247], v[114:117], v[64:79]
	v_exp_f32_e32 v244, v94
	v_add_f32_e32 v80, v238, v80
	v_add_f32_e32 v80, v239, v80
	v_add_f32_e32 v80, v240, v80
	v_add_f32_e32 v80, v241, v80
	v_add_f32_e32 v80, v244, v80
	v_add_f32_e32 v204, v95, v80
	v_mov_b32_e32 v205, v204
	v_cvt_pk_bf16_f32 v80, v219, v221
	v_cvt_pk_bf16_f32 v81, v217, v220
	v_cvt_pk_bf16_f32 v82, v215, v218
	v_cvt_pk_bf16_f32 v83, v214, v216
	v_cvt_pk_bf16_f32 v84, v211, v213
	v_cvt_pk_bf16_f32 v85, v209, v212
	v_cvt_pk_bf16_f32 v86, v207, v210
	v_cvt_pk_bf16_f32 v87, v206, v208
	v_cvt_pk_bf16_f32 v88, v222, v223
	v_cvt_pk_bf16_f32 v89, v224, v225
	v_cvt_pk_bf16_f32 v90, v226, v227
	v_cvt_pk_bf16_f32 v91, v234, v235
	v_cvt_pk_bf16_f32 v92, v236, v237
	v_cvt_pk_bf16_f32 v93, v238, v239
	v_cvt_pk_bf16_f32 v94, v240, v241
	v_cvt_pk_bf16_f32 v95, v244, v95
	v_permlane32_swap_b32_e32 v204, v205
	v_permlane32_swap_b32_e32 v80, v82
	v_permlane32_swap_b32_e32 v81, v83
	v_permlane32_swap_b32_e32 v84, v86
	v_permlane32_swap_b32_e32 v85, v87
	v_permlane32_swap_b32_e32 v88, v90
	v_permlane32_swap_b32_e32 v89, v91
	v_permlane32_swap_b32_e32 v92, v94
	v_permlane32_swap_b32_e32 v93, v95
	s_cmp_ge_u32 s40, s39
	s_cselect_b64 s[18:19], -1, 0
	s_and_b64 vcc, exec, s[18:19]
	s_cbranch_vccnz .Ldiff_pf_skip
	global_load_dwordx4 v[130:133], v[172:173], off
	v_lshl_add_u64 v[174:175], v[172:173], 0, s[34:35]
	global_load_dwordx4 v[134:137], v[174:175], off
	global_load_dwordx4 v[138:141], v[170:171], off offset:2048
	v_lshl_add_u64 v[172:173], v[172:173], 0, s[46:47]
	v_lshl_add_u64 v[170:171], v[170:171], 0, s[46:47]
